# attention work queue: FoX/SWA items interleaved with the second half of MLA items (low-power items beside MFMA-bound items)
# baseline (speedup 1.0000x reference)
; __device__ __forceinline__ void attn_phase(KArgsP ka, unsigned char* ws, const float* sinks, int l, int cidx, LAS unsigned char* lds) {
;     ...
;         int idx = *slot;
;         if (DEFER_L1 && l == 0) {
;             if (idx >= 6 * NCV + (1536 - 5 * NCV)) break;
;             if (idx < 6 * NCV) { const int g = idx / 6, pos = idx - 6 * g; if (pos == 5) { conv_item(ka, ws, g, lds); continue; } idx = 5 * g + pos; }
;             else idx = 5 * NCV + (idx - 6 * NCV);
;         }
;         if (idx >= 1536) break;
;         const int kind = idx >> 9, r = idx & 511, qb = 31 - (r >> 4), bh = r & 15, b = bh >> 3, h = bh & 7;
;     ...
;         if (kind == 0)
;             attn_item<192, 128, 128, 0>(mQM(B) + h * 192, 1536, mKM(B) + h * 128, 1024, mKPE(B), mVM(B) + h * 128, 1024, mMIX(B) + h * 128, nullptr, nullptr, h, 0.f, b, qb, lds);
;         else
;     ...
;         if (kind == 1)
;             attn_item<64, 64, 64, 1>(mQF(B) + h * 64, 512, mKF(B) + h * 64, 512, nullptr, mVF(B) + h * 64, 512, mMIX(B) + 1536 + h * 64, mCUM(B), mCHS(B), h, 0.f, b, qb, lds);
;         else
;             attn_item<64, 64, 64, 2>(mQS(B) + h * 64, 512, mKS(B) + (h >> 2) * 64, 128, nullptr, mVS(B) + (h >> 2) * 64, 128, mMIX(B) + 1024 + h * 64, nullptr, nullptr, h, sinks[h] * LOG2E, b, qb, lds);
.LBB0_289:
	s_cmpk_lt_i32 s35, 0x600
	s_cbranch_scc0 .LBB0_93
	s_cmpk_lt_i32 s35, 0x100
	s_cbranch_scc1 .Lremap_done
	s_add_i32 s2, s35, 0xffffff00
	s_mul_hi_u32 s3, s2, 0x33333334
	s_mul_i32 s35, s3, 5
	s_sub_i32 s2, s2, s35
	s_cmp_eq_u32 s2, 0
	s_cbranch_scc1 .Lremap_mla
	s_lshl_b32 s35, s3, 1
	s_add_i32 s35, s35, s2
	s_cmp_le_u32 s2, 2
	s_cbranch_scc1 .Lremap_fox
	s_addk_i32 s35, 0x3fd
	s_branch .Lremap_done
.Lremap_fox:
	s_addk_i32 s35, 0x1ff
	s_branch .Lremap_done
.Lremap_mla:
	s_add_i32 s35, s3, 0x100
.Lremap_done:
	s_not_b32 s2, s35
	s_bfe_u32 s52, s2, 0x50004
	s_bfe_u32 s53, s35, 0x10003
	s_and_b32 s54, s35, 7
	s_mov_b64 s[78:79], 0x800
	s_cmpk_gt_u32 s35, 0x1ff
	s_mov_b64 s[2:3], -1
	s_cbranch_scc0 .LBB0_385
	s_and_b32 s2, s35, 0xfffffe00
	s_lshl_b32 s28, s54, 6
	s_cmpk_lg_i32 s2, 0x200
	s_mov_b64 s[2:3], -1
	s_cbranch_scc0 .LBB0_324
	s_lshl_b32 s20, s28, 1
	v_readlane_b32 s2, v254, 30
	s_add_u32 s2, s2, s20
	v_readlane_b32 s3, v254, 31
	s_addc_u32 s3, s3, 0
	s_lshl_b32 s8, s54, 4
	s_and_b32 s8, s8, 64
	s_lshl_b32 s14, s8, 1
	v_readlane_b32 s8, v254, 32
	s_add_u32 s8, s8, s14
	v_readlane_b32 s9, v254, 34
	s_addc_u32 s9, s9, 0
	s_lshl_b32 s10, s54, 2
	v_mov_b32_e32 v1, s10
	v_readlane_b32 s10, v254, 28
	v_readlane_b32 s11, v254, 29
	v_mov_b32_e32 v38, v218
	s_mov_b64 s[26:27], s[62:63]
	s_lshl_b32 s36, s53, 13
	s_lshl_b32 s62, s52, 2
	s_nop 0
	global_load_dword v1, v1, s[10:11]
	s_lshl_b32 s10, s52, 8
	v_readfirstlane_b32 s63, v38
	s_ashr_i32 s55, s63, 6
	s_lshl_b32 s21, s55, 5
	v_and_b32_e32 v8, 31, v38
	s_add_i32 s21, s21, s10
	v_or_b32_e32 v100, s21, v8
	v_ashrrev_i32_e32 v101, 31, v100
	v_lshl_add_u64 v[98:99], v[100:101], 0, s[36:37]
	v_bfe_u32 v39, v38, 5, 1
	v_lshlrev_b64 v[2:3], 10, v[98:99]
	v_lshl_add_u64 v[4:5], s[2:3], 0, v[2:3]
	v_lshlrev_b32_e32 v2, 4, v39
	v_mov_b32_e32 v3, v0
	v_lshl_add_u64 v[4:5], v[4:5], 0, v[2:3]
	global_load_dwordx4 v[82:85], v[4:5], off
	global_load_dwordx4 v[86:89], v[4:5], off offset:32
	global_load_dwordx4 v[90:93], v[4:5], off offset:64
	global_load_dwordx4 v[94:97], v[4:5], off offset:96
	v_sub_u32_e64 v3, s62, 2 clamp
	v_lshlrev_b32_e32 v3, 13, v3
	s_lshl_b32 s2, s53, 20
	v_or_b32_e32 v3, s2, v3
	v_lshlrev_b32_e32 v4, 1, v3
	v_mov_b32_e32 v5, v0
	s_cmp_lt_i32 s55, 9
	v_and_b32_e32 v37, 63, v38
	s_cselect_b64 s[10:11], -1, 0
	s_cmp_gt_i32 s55, 8
	v_lshl_add_u64 v[6:7], s[8:9], 0, v[4:5]
	s_cbranch_scc1 .LBB0_294
	s_and_b32 s2, s63, 0xffffffc0
	v_or_b32_e32 v10, s2, v37
	v_mul_hi_i32 v3, v10, s81
	v_lshrrev_b32_e32 v5, 31, v3
	v_ashrrev_i32_e32 v3, 1, v3
	v_add_u32_e32 v3, v3, v5
	v_mad_u64_u32 v[10:11], s[2:3], v3, -9, v[10:11]
	v_min_i32_e32 v5, 7, v10
	v_lshlrev_b32_e32 v3, 7, v3
	v_lshl_add_u32 v10, v5, 3, v3
	v_mov_b32_e32 v11, v0
	s_lshl_b32 s2, s55, 10
	v_lshl_add_u64 v[10:11], v[10:11], 1, v[6:7]
	s_add_i32 m0, s2, 0
	s_nop 0
	global_load_lds_dwordx4 v[10:11], off
